# P5 LayerNorm loop: gamma/beta loads hoisted out of the token loop, next token row prefetched into spare VGPRs (no per-chunk vmcnt(0) ladder)
# speedup vs baseline: 1.0036x; 1.0036x over previous
.LBB0_519:
	s_or_b64 exec, exec, s[0:1]
	v_mov_b32_e32 v8, v160
	s_and_b64 vcc, exec, s[70:71]
	s_waitcnt lgkmcnt(0)
	s_barrier
	s_cbranch_vccz .LBB0_523
	v_mbcnt_hi_u32_b32 v0, -1, v186
	v_and_b32_e32 v1, 64, v0
	v_add_u32_e32 v1, 64, v1
	v_xor_b32_e32 v2, 1, v0
	v_cmp_lt_i32_e32 vcc, v2, v1
	s_ashr_i32 s47, s46, 31
	v_ashrrev_i32_e32 v9, 31, v8
	v_cndmask_b32_e32 v2, v0, v2, vcc
	v_lshlrev_b32_e32 v12, 2, v2
	v_xor_b32_e32 v2, 2, v0
	v_cmp_lt_i32_e32 vcc, v2, v1
	v_readlane_b32 s16, v234, 7
	s_lshl_b64 s[0:1], s[46:47], 10
	v_cndmask_b32_e32 v2, v0, v2, vcc
	v_lshlrev_b32_e32 v13, 2, v2
	v_xor_b32_e32 v2, 4, v0
	v_cmp_lt_i32_e32 vcc, v2, v1
	v_lshlrev_b64 v[6:7], 4, v[8:9]
	v_readlane_b32 s28, v234, 19
	v_cndmask_b32_e32 v2, v0, v2, vcc
	v_lshlrev_b32_e32 v14, 2, v2
	v_xor_b32_e32 v2, 8, v0
	v_cmp_lt_i32_e32 vcc, v2, v1
	v_readlane_b32 s29, v234, 20
	v_readlane_b32 s30, v234, 21
	v_cndmask_b32_e32 v2, v0, v2, vcc
	v_lshlrev_b32_e32 v15, 2, v2
	v_xor_b32_e32 v2, 16, v0
	v_cmp_lt_i32_e32 vcc, v2, v1
	v_readlane_b32 s31, v234, 22
	v_lshl_add_u64 v[4:5], v[8:9], 2, s[0:1]
	v_cndmask_b32_e32 v2, v0, v2, vcc
	v_lshlrev_b32_e32 v16, 2, v2
	v_xor_b32_e32 v2, 32, v0
	v_cmp_lt_i32_e32 vcc, v2, v1
	s_lshl_b64 s[0:1], s[46:47], 12
	s_ashr_i32 s81, s80, 31
	v_cndmask_b32_e32 v0, v0, v2, vcc
	v_lshlrev_b32_e32 v17, 2, v0
	v_lshl_add_u64 v[0:1], s[28:29], 0, v[6:7]
	v_lshl_add_u64 v[2:3], s[30:31], 0, v[6:7]
	v_lshl_add_u64 v[6:7], s[0:1], 0, v[6:7]
	s_lshl_b64 s[0:1], s[46:47], 11
	v_readlane_b32 s17, v234, 8
	s_lshl_b64 s[4:5], s[80:81], 10
	s_lshl_b64 s[6:7], s[80:81], 12
	v_lshl_add_u64 v[8:9], v[8:9], 3, s[0:1]
	s_lshl_b64 s[8:9], s[80:81], 11
	s_mov_b32 s10, 0x3fb504f3
	v_mov_b32_e32 v18, 0x3727c5ac
	s_mov_b32 s3, 0xf800000
	v_mov_b32_e32 v19, 0x260
	s_mov_b32 s11, 0x10400000
	s_mov_b32 s12, 0xc3e00000
	v_mov_b32_e32 v20, 0x43e00000
	s_mov_b32 s13, 0xe400000
	s_mov_b32 s14, s46
	v_readlane_b32 s18, v234, 9
	v_readlane_b32 s19, v234, 10
	v_readlane_b32 s20, v234, 11
	v_readlane_b32 s21, v234, 12
	v_readlane_b32 s22, v234, 13
	v_readlane_b32 s23, v234, 14
	v_readlane_b32 s24, v234, 15
	v_readlane_b32 s25, v234, 16
	v_readlane_b32 s26, v234, 17
	v_readlane_b32 s27, v234, 18
	global_load_dwordx4 v[64:67], v[0:1], off
	global_load_dwordx4 v[68:71], v[0:1], off offset:1024
	global_load_dwordx4 v[72:75], v[0:1], off offset:2048
	global_load_dwordx4 v[76:79], v[0:1], off offset:3072
	global_load_dwordx4 v[80:83], v[2:3], off
	global_load_dwordx4 v[84:87], v[2:3], off offset:1024
	global_load_dwordx4 v[88:91], v[2:3], off offset:2048
	global_load_dwordx4 v[92:95], v[2:3], off offset:3072
	s_add_u32 s98, s84, 0x14400000
	s_addc_u32 s99, s85, 0
	s_add_u32 s100, s84, 0x10400000
	s_addc_u32 s101, s85, 0
	v_lshl_add_u64 v[124:125], s[16:17], 0, v[6:7]
	v_lshl_add_u64 v[126:127], s[98:99], 0, v[8:9]
	global_load_dwordx4 v[100:103], v[124:125], off
	global_load_dwordx4 v[104:107], v[124:125], off offset:1024
	global_load_dwordx4 v[108:111], v[124:125], off offset:2048
	global_load_dwordx4 v[112:115], v[124:125], off offset:3072
	global_load_dwordx2 v[116:117], v[126:127], off
	global_load_dwordx2 v[118:119], v[126:127], off offset:512
	global_load_dwordx2 v[120:121], v[126:127], off offset:1024
	global_load_dwordx2 v[122:123], v[126:127], off offset:1536
	s_waitcnt vmcnt(0)
.LBB0_521:
	s_waitcnt vmcnt(8)
	v_lshl_add_u64 v[10:11], s[100:101], 0, v[6:7]
	s_add_i32 s14, s14, s80
	v_lshl_add_u64 v[6:7], v[6:7], 0, s[6:7]
	v_lshl_add_u64 v[8:9], v[8:9], 0, s[8:9]
	s_cmpk_lt_i32 s14, 0x4000
	v_lshlrev_b32_e32 v54, 16, v116
	v_and_b32_e32 v55, 0xffff0000, v116
	v_lshlrev_b32_e32 v48, 16, v117
	v_and_b32_e32 v49, 0xffff0000, v117
	v_lshlrev_b32_e32 v56, 16, v118
	v_and_b32_e32 v57, 0xffff0000, v118
	v_lshlrev_b32_e32 v50, 16, v119
	v_and_b32_e32 v51, 0xffff0000, v119
	v_lshlrev_b32_e32 v58, 16, v120
	v_and_b32_e32 v59, 0xffff0000, v120
	v_lshlrev_b32_e32 v52, 16, v121
	v_and_b32_e32 v53, 0xffff0000, v121
	v_lshlrev_b32_e32 v60, 16, v122
	v_and_b32_e32 v61, 0xffff0000, v122
	v_lshlrev_b32_e32 v46, 16, v123
	v_and_b32_e32 v47, 0xffff0000, v123
	v_pk_fma_f32 v[32:33], v[102:103], s[10:11], v[48:49] op_sel_hi:[1,0,1]
	v_pk_fma_f32 v[30:31], v[100:101], s[10:11], v[54:55] op_sel_hi:[1,0,1]
	v_pk_fma_f32 v[36:37], v[106:107], s[10:11], v[50:51] op_sel_hi:[1,0,1]
	v_pk_fma_f32 v[34:35], v[104:105], s[10:11], v[56:57] op_sel_hi:[1,0,1]
	v_pk_fma_f32 v[40:41], v[110:111], s[10:11], v[52:53] op_sel_hi:[1,0,1]
	v_pk_fma_f32 v[44:45], v[114:115], s[10:11], v[46:47] op_sel_hi:[1,0,1]
	v_pk_fma_f32 v[38:39], v[108:109], s[10:11], v[58:59] op_sel_hi:[1,0,1]
	v_pk_fma_f32 v[42:43], v[112:113], s[10:11], v[60:61] op_sel_hi:[1,0,1]
	s_cbranch_scc0 .Lln5_skip
	v_lshl_add_u64 v[124:125], s[16:17], 0, v[6:7]
	v_lshl_add_u64 v[126:127], s[98:99], 0, v[8:9]
	global_load_dwordx4 v[100:103], v[124:125], off
	global_load_dwordx4 v[104:107], v[124:125], off offset:1024
	global_load_dwordx4 v[108:111], v[124:125], off offset:2048
	global_load_dwordx4 v[112:115], v[124:125], off offset:3072
	global_load_dwordx2 v[116:117], v[126:127], off
	global_load_dwordx2 v[118:119], v[126:127], off offset:512
	global_load_dwordx2 v[120:121], v[126:127], off offset:1024
	global_load_dwordx2 v[122:123], v[126:127], off offset:1536
.Lln5_skip:
	v_pk_mov_b32 v[46:47], v[30:31], v[32:33] op_sel:[1,0]
	v_mov_b32_e32 v48, v30
	v_mov_b32_e32 v49, v33
	v_pk_mov_b32 v[50:51], v[34:35], v[36:37] op_sel:[1,0]
	v_mov_b32_e32 v52, v34
	v_mov_b32_e32 v53, v37
	v_pk_add_f32 v[46:47], v[46:47], v[48:49]
	v_pk_add_f32 v[48:49], v[50:51], v[52:53]
	v_add_f32_e32 v21, v46, v47
	v_pk_add_f32 v[46:47], v[48:49], v[48:49] op_sel:[0,1] op_sel_hi:[1,0]
	v_add_f32_e32 v54, v38, v39
	v_add_f32_e32 v56, v40, v41
	v_mov_b32_e32 v59, v42
	v_mov_b32_e32 v55, v44
	v_mov_b32_e32 v57, v45
	v_add_f32_e32 v58, 0, v21
	v_mov_b32_e32 v47, v43
	v_pk_add_f32 v[50:51], v[54:55], v[56:57]
	v_pk_add_f32 v[46:47], v[58:59], v[46:47]
	s_nop 0
	v_pk_add_f32 v[46:47], v[46:47], v[50:51]
	s_nop 0
	v_add_f32_e32 v21, v46, v47
	ds_bpermute_b32 v46, v12, v21
	s_waitcnt lgkmcnt(0)
	v_add_f32_e32 v21, v21, v46
	ds_bpermute_b32 v46, v13, v21
	s_waitcnt lgkmcnt(0)
	v_add_f32_e32 v21, v21, v46
	ds_bpermute_b32 v46, v14, v21
	s_waitcnt lgkmcnt(0)
	v_add_f32_e32 v21, v21, v46
	ds_bpermute_b32 v46, v15, v21
	s_waitcnt lgkmcnt(0)
	v_add_f32_e32 v21, v21, v46
	ds_bpermute_b32 v46, v16, v21
	s_waitcnt lgkmcnt(0)
	v_add_f32_e32 v21, v21, v46
	ds_bpermute_b32 v46, v17, v21
	s_waitcnt lgkmcnt(0)
	v_add_f32_e32 v21, v21, v46
	v_fmamk_f32 v31, v21, 0xba800000, v31
	v_fmac_f32_e32 v30, 0xba800000, v21
	v_fmamk_f32 v33, v21, 0xba800000, v33
	v_fmac_f32_e32 v32, 0xba800000, v21
	v_fmamk_f32 v35, v21, 0xba800000, v35
	v_fmac_f32_e32 v34, 0xba800000, v21
	v_fmamk_f32 v37, v21, 0xba800000, v37
	v_fmac_f32_e32 v36, 0xba800000, v21
	v_pk_mul_f32 v[46:47], v[32:33], v[32:33]
	v_pk_mul_f32 v[48:49], v[30:31], v[30:31]
	v_pk_mul_f32 v[50:51], v[36:37], v[36:37]
	v_pk_mul_f32 v[52:53], v[34:35], v[34:35]
	v_fmac_f32_e32 v38, 0xba800000, v21
	v_fmac_f32_e32 v40, 0xba800000, v21
	v_pk_mov_b32 v[58:59], v[48:49], v[46:47] op_sel:[1,0]
	v_mov_b32_e32 v49, v47
	v_pk_mov_b32 v[46:47], v[52:53], v[50:51] op_sel:[1,0]
	v_mov_b32_e32 v53, v51
	v_fmamk_f32 v39, v21, 0xba800000, v39
	v_fmamk_f32 v41, v21, 0xba800000, v41
	v_mul_f32_e32 v54, v38, v38
	v_mul_f32_e32 v56, v40, v40
	v_pk_add_f32 v[48:49], v[58:59], v[48:49]
	v_pk_add_f32 v[46:47], v[46:47], v[52:53]
	v_fmamk_f32 v45, v21, 0xba800000, v45
	v_fmac_f32_e32 v44, 0xba800000, v21
	v_fmamk_f32 v43, v21, 0xba800000, v43
	v_fmac_f32_e32 v42, 0xba800000, v21
	v_pk_fma_f32 v[50:51], v[38:39], v[38:39], v[54:55] op_sel_hi:[1,1,0]
	v_pk_fma_f32 v[54:55], v[40:41], v[40:41], v[56:57] op_sel_hi:[1,1,0]
	v_pk_add_f32 v[48:49], v[48:49], v[48:49] op_sel_hi:[0,1]
	v_pk_add_f32 v[46:47], v[46:47], v[46:47] op_sel_hi:[0,1]
	v_mul_f32_e32 v50, v42, v42
	v_mul_f32_e32 v54, v43, v43
	v_mul_f32_e32 v48, v44, v44
	v_mul_f32_e32 v46, v45, v45
	v_pk_add_f32 v[50:51], v[50:51], v[54:55]
	v_pk_add_f32 v[46:47], v[48:49], v[46:47]
	s_nop 0
	v_pk_add_f32 v[46:47], v[50:51], v[46:47]
	v_mov_b32_e32 v51, 0
	v_add_f32_e32 v21, v46, v47
	ds_bpermute_b32 v46, v12, v21
	s_waitcnt lgkmcnt(0)
	v_add_f32_e32 v21, v21, v46
	ds_bpermute_b32 v46, v13, v21
	s_waitcnt lgkmcnt(0)
	v_add_f32_e32 v21, v21, v46
	ds_bpermute_b32 v46, v14, v21
	s_waitcnt lgkmcnt(0)
	v_add_f32_e32 v21, v21, v46
	ds_bpermute_b32 v46, v15, v21
	s_waitcnt lgkmcnt(0)
	v_add_f32_e32 v21, v21, v46
	ds_bpermute_b32 v46, v16, v21
	s_waitcnt lgkmcnt(0)
	v_add_f32_e32 v21, v21, v46
	ds_bpermute_b32 v46, v17, v21
	s_waitcnt lgkmcnt(0)
	v_add_f32_e32 v21, v21, v46
	v_fmamk_f32 v21, v21, 0x3a800000, v18
	v_mul_f32_e32 v46, 0x4f800000, v21
	v_cmp_gt_f32_e32 vcc, s3, v21
	s_nop 1
	v_cndmask_b32_e32 v21, v21, v46, vcc
	v_sqrt_f32_e32 v46, v21
	s_nop 0
	v_add_u32_e32 v47, -1, v46
	v_add_u32_e32 v48, 1, v46
	v_fma_f32 v49, -v47, v46, v21
	v_fma_f32 v50, -v48, v46, v21
	v_cmp_ge_f32_e64 s[0:1], 0, v49
	s_nop 1
	v_cndmask_b32_e64 v46, v46, v47, s[0:1]
	v_cmp_lt_f32_e64 s[0:1], 0, v50
	s_nop 1
	v_cndmask_b32_e64 v46, v46, v48, s[0:1]
	v_mul_f32_e32 v47, 0x37800000, v46
	v_cndmask_b32_e32 v46, v46, v47, vcc
	v_cmp_class_f32_e32 vcc, v21, v19
	s_nop 1
	v_cndmask_b32_e32 v21, v46, v21, vcc
	v_div_scale_f32 v46, s[0:1], v21, v21, 1.0
	v_rcp_f32_e32 v48, v46
	v_div_scale_f32 v47, vcc, 1.0, v21, 1.0
	v_fma_f32 v49, -v46, v48, 1.0
	v_fmac_f32_e32 v48, v49, v48
	v_mul_f32_e32 v49, v47, v48
	v_fma_f32 v50, -v46, v49, v47
	v_fmac_f32_e32 v49, v50, v48
	v_fma_f32 v46, -v46, v49, v47
	v_div_fmas_f32 v46, v46, v48, v49
	v_div_fixup_f32 v46, v46, v21, 1.0
	v_pk_mul_f32 v[30:31], v[30:31], v[46:47] op_sel_hi:[1,0]
	v_pk_mul_f32 v[32:33], v[32:33], v[46:47] op_sel_hi:[1,0]
	v_pk_fma_f32 v[22:23], v[64:65], v[30:31], v[80:81]
	v_pk_fma_f32 v[24:25], v[66:67], v[32:33], v[82:83]
	global_store_dwordx4 v[10:11], v[22:25], off
	v_pk_mul_f32 v[34:35], v[34:35], v[46:47] op_sel_hi:[1,0]
	v_pk_mul_f32 v[36:37], v[36:37], v[46:47] op_sel_hi:[1,0]
	v_pk_mul_f32 v[38:39], v[38:39], v[46:47] op_sel_hi:[1,0]
	v_pk_mul_f32 v[40:41], v[40:41], v[46:47] op_sel_hi:[1,0]
	v_mov_b32_e32 v21, 0
	v_med3_f32 v22, v22, s12, v20
	v_med3_f32 v23, v23, s12, v20
	v_mov_b32_e32 v47, 0
	v_cvt_pk_fp8_f32 v21, v22, v23
	v_mov_b32_e32 v50, 0
	v_pk_mul_f32 v[42:43], v[42:43], v[46:47] op_sel_hi:[1,0]
	v_pk_mul_f32 v[44:45], v[44:45], v[46:47] op_sel_hi:[1,0]
	v_med3_f32 v24, v24, s12, v20
	v_med3_f32 v25, v25, s12, v20
	v_cvt_pk_fp8_f32 v21, v24, v25 op_sel:[0,0,1]
	v_lshl_add_u64 v[48:49], s[84:85], 0, v[4:5]
	v_add_co_u32_e32 v48, vcc, s13, v48
	v_lshl_add_u64 v[4:5], v[4:5], 0, s[4:5]
	s_nop 0
	v_addc_co_u32_e32 v49, vcc, 0, v49, vcc
	v_pk_fma_f32 v[28:29], v[70:71], v[36:37], v[86:87]
	v_pk_fma_f32 v[26:27], v[68:69], v[34:35], v[84:85]
	global_store_dwordx4 v[10:11], v[26:29], off offset:1024
	v_med3_f32 v22, v26, s12, v20
	v_med3_f32 v23, v27, s12, v20
	v_cvt_pk_fp8_f32 v47, v22, v23
	v_med3_f32 v24, v28, s12, v20
	v_med3_f32 v25, v29, s12, v20
	v_cvt_pk_fp8_f32 v47, v24, v25 op_sel:[0,0,1]
	v_pk_fma_f32 v[32:33], v[74:75], v[40:41], v[90:91]
	v_pk_fma_f32 v[30:31], v[72:73], v[38:39], v[88:89]
	global_store_dwordx4 v[10:11], v[30:33], off offset:2048
	v_med3_f32 v22, v30, s12, v20
	v_med3_f32 v23, v31, s12, v20
	v_cvt_pk_fp8_f32 v50, v22, v23
	v_med3_f32 v24, v32, s12, v20
	v_med3_f32 v25, v33, s12, v20
	v_cvt_pk_fp8_f32 v50, v24, v25 op_sel:[0,0,1]
	v_pk_fma_f32 v[22:23], v[76:77], v[42:43], v[92:93]
	s_nop 0
	v_med3_f32 v26, v22, s12, v20
	v_med3_f32 v27, v23, s12, v20
	v_cvt_pk_fp8_f32 v51, v26, v27
	v_pk_fma_f32 v[24:25], v[78:79], v[44:45], v[94:95]
	global_store_dwordx4 v[10:11], v[22:25], off offset:3072
	v_med3_f32 v10, v24, s12, v20
	v_med3_f32 v11, v25, s12, v20
	v_cvt_pk_fp8_f32 v51, v10, v11 op_sel:[0,0,1]
	global_store_dword v[48:49], v21, off
	global_store_dword v[48:49], v47, off offset:256
	global_store_dword v[48:49], v50, off offset:512
	global_store_dword v[48:49], v51, off offset:768
	s_cbranch_scc1 .LBB0_521
	v_readlane_b32 s81, v234, 49

	.amdhsa_kernel _Z14fwd_megakernel4Ptrs
		.amdhsa_group_segment_fixed_size 0
		.amdhsa_private_segment_fixed_size 0
		.amdhsa_kernarg_size 392
		.amdhsa_user_sgpr_count 2
		.amdhsa_user_sgpr_dispatch_ptr 0
		.amdhsa_user_sgpr_queue_ptr 0
		.amdhsa_user_sgpr_kernarg_segment_ptr 1
		.amdhsa_user_sgpr_dispatch_id 0
		.amdhsa_user_sgpr_kernarg_preload_length 0
		.amdhsa_user_sgpr_kernarg_preload_offset 0
		.amdhsa_user_sgpr_private_segment_size 0
		.amdhsa_uses_dynamic_stack 0
		.amdhsa_enable_private_segment 0
		.amdhsa_system_sgpr_workgroup_id_x 1
		.amdhsa_system_sgpr_workgroup_id_y 0
		.amdhsa_system_sgpr_workgroup_id_z 0
		.amdhsa_system_sgpr_workgroup_info 0
		.amdhsa_system_vgpr_workitem_id 2
		.amdhsa_next_free_vgpr 235
		.amdhsa_next_free_sgpr 102
		.amdhsa_accum_offset 236
		.amdhsa_reserve_vcc 1
		.amdhsa_float_round_mode_32 0
		.amdhsa_float_round_mode_16_64 0
		.amdhsa_float_denorm_mode_32 3
		.amdhsa_float_denorm_mode_16_64 3
		.amdhsa_dx10_clamp 1
		.amdhsa_ieee_mode 1
		.amdhsa_fp16_overflow 0
		.amdhsa_tg_split 0
		.amdhsa_exception_fp_ieee_invalid_op 0
		.amdhsa_exception_fp_denorm_src 0
		.amdhsa_exception_fp_ieee_div_zero 0
		.amdhsa_exception_fp_ieee_overflow 0
		.amdhsa_exception_fp_ieee_underflow 0
		.amdhsa_exception_fp_ieee_inexact 0
		.amdhsa_exception_int_div_zero 0
	.end_amdhsa_kernel

.Lfunc_end0:
	.size	_Z14fwd_megakernel4Ptrs, .Lfunc_end0-_Z14fwd_megakernel4Ptrs
	.set _Z14fwd_megakernel4Ptrs.num_vgpr, 235
	.set _Z14fwd_megakernel4Ptrs.num_agpr, 0
	.set _Z14fwd_megakernel4Ptrs.numbered_sgpr, 102
	.set _Z14fwd_megakernel4Ptrs.num_named_barrier, 0
	.set _Z14fwd_megakernel4Ptrs.private_seg_size, 0
	.set _Z14fwd_megakernel4Ptrs.uses_vcc, 1
	.set _Z14fwd_megakernel4Ptrs.uses_flat_scratch, 0
	.set _Z14fwd_megakernel4Ptrs.has_dyn_sized_stack, 0
	.set _Z14fwd_megakernel4Ptrs.has_recursion, 0
	.set _Z14fwd_megakernel4Ptrs.has_indirect_call, 0

amdhsa.kernels:
  - .agpr_count:     0
    .args:
      - .offset:         0
        .size:           136
        .value_kind:     by_value
      - .offset:         136
        .size:           4
        .value_kind:     hidden_block_count_x
      - .offset:         140
        .size:           4
        .value_kind:     hidden_block_count_y
      - .offset:         144
        .size:           4
        .value_kind:     hidden_block_count_z
      - .offset:         148
        .size:           2
        .value_kind:     hidden_group_size_x
      - .offset:         150
        .size:           2
        .value_kind:     hidden_group_size_y
      - .offset:         152
        .size:           2
        .value_kind:     hidden_group_size_z
      - .offset:         154
        .size:           2
        .value_kind:     hidden_remainder_x
      - .offset:         156
        .size:           2
        .value_kind:     hidden_remainder_y
      - .offset:         158
        .size:           2
        .value_kind:     hidden_remainder_z
      - .offset:         176
        .size:           8
        .value_kind:     hidden_global_offset_x
      - .offset:         184
        .size:           8
        .value_kind:     hidden_global_offset_y
      - .offset:         192
        .size:           8
        .value_kind:     hidden_global_offset_z
      - .offset:         200
        .size:           2
        .value_kind:     hidden_grid_dims
      - .offset:         224
        .size:           8
        .value_kind:     hidden_multigrid_sync_arg
      - .offset:         256
        .size:           4
        .value_kind:     hidden_dynamic_lds_size
    .group_segment_fixed_size: 0
    .kernarg_segment_align: 8
    .kernarg_segment_size: 392
    .language:       OpenCL C
    .language_version:
      - 2
      - 0
    .max_flat_workgroup_size: 512
    .name:           _Z14fwd_megakernel4Ptrs
    .private_segment_fixed_size: 0
    .sgpr_count:     108
    .sgpr_spill_count: 58
    .symbol:         _Z14fwd_megakernel4Ptrs.kd
    .uniform_work_group_size: 1
    .uses_dynamic_stack: false
    .vgpr_count:     235
    .vgpr_spill_count: 0
    .wavefront_size: 64
